# attention S = K.Q^T: all eight K-fragment LDS reads of a tile issued up front into free registers, MFMAs behind counted lgkmcnt waits (no WAR s_nop padding)
# baseline (speedup 1.0000x reference)
.LBB0_373:
	s_and_b32 s33, s42, 1
	s_mul_i32 s36, s33, 0x1200
	v_lshl_add_u32 v84, s36, 1, v134
	ds_read_b128 v[152:155], v84
	ds_read_b128 v[160:163], v84 offset:2304
	ds_read_b128 v[156:159], v84 offset:64
	ds_read_b128 v[164:167], v84 offset:2368
	ds_read_b128 v[168:171], v84 offset:4608
	ds_read_b128 v[176:179], v84 offset:6912
	ds_read_b128 v[172:175], v84 offset:4672
	ds_read_b128 v[180:183], v84 offset:6976
	s_cmp_lt_i32 s42, s27
	s_cselect_b64 s[0:1], -1, 0
	s_and_b64 s[0:1], s[18:19], s[0:1]
	s_andn2_b64 vcc, exec, s[0:1]
	s_waitcnt lgkmcnt(7)
	v_mfma_f32_16x16x32_bf16 v[80:83], v[152:155], v[16:19], 0
	v_mfma_f32_16x16x32_bf16 v[64:67], v[152:155], v[24:27], 0
	s_waitcnt lgkmcnt(6)
	v_mfma_f32_16x16x32_bf16 v[72:75], v[160:163], v[16:19], 0
	v_mfma_f32_16x16x32_bf16 v[68:71], v[160:163], v[24:27], 0
	s_waitcnt lgkmcnt(5)
	v_mfma_f32_16x16x32_bf16 v[80:83], v[156:159], v[20:23], v[80:83]
	v_mfma_f32_16x16x32_bf16 v[64:67], v[156:159], v[28:31], v[64:67]
	s_waitcnt lgkmcnt(4)
	v_mfma_f32_16x16x32_bf16 v[72:75], v[164:167], v[20:23], v[72:75]
	v_mfma_f32_16x16x32_bf16 v[68:71], v[164:167], v[28:31], v[68:71]
	s_waitcnt lgkmcnt(3)
	v_mfma_f32_16x16x32_bf16 v[76:79], v[168:171], v[16:19], 0
	v_mfma_f32_16x16x32_bf16 v[60:63], v[168:171], v[24:27], 0
	s_waitcnt lgkmcnt(2)
	v_mfma_f32_16x16x32_bf16 v[84:87], v[176:179], v[16:19], 0
	v_mfma_f32_16x16x32_bf16 v[56:59], v[176:179], v[24:27], 0
	s_waitcnt lgkmcnt(1)
	v_mfma_f32_16x16x32_bf16 v[76:79], v[172:175], v[20:23], v[76:79]
	v_mfma_f32_16x16x32_bf16 v[60:63], v[172:175], v[28:31], v[60:63]
	s_waitcnt lgkmcnt(0)
	v_mfma_f32_16x16x32_bf16 v[84:87], v[180:183], v[20:23], v[84:87]
	v_mfma_f32_16x16x32_bf16 v[56:59], v[180:183], v[28:31], v[56:59]
	s_cbranch_vccnz .LBB0_376
	s_cmp_lt_i32 s25, s16
	s_cselect_b64 s[0:1], -1, 0
	s_cmp_gt_i32 s25, s30
	s_cselect_b64 s[42:43], -1, 0
	s_or_b64 s[0:1], s[0:1], s[42:43]
	s_andn2_b64 vcc, exec, s[0:1]
	s_cbranch_vccnz .LBB0_376
	v_add_u32_e32 v107, 51, v138
	v_cmp_gt_u32_e32 vcc, s34, v107
	v_add_u32_e32 v107, 50, v138
	v_cmp_gt_u32_e64 s[0:1], s34, v107
	v_add_u32_e32 v107, 49, v138
	v_cmp_gt_u32_e64 s[42:43], s34, v107
	v_add_u32_e32 v107, 48, v138
	v_cmp_gt_u32_e64 s[44:45], s34, v107
	v_add_u32_e32 v107, 35, v138
	v_cmp_gt_u32_e64 s[46:47], s34, v107
	v_add_u32_e32 v107, 34, v138
	v_cmp_gt_u32_e64 s[48:49], s34, v107
	v_add_u32_e32 v107, 33, v138
	v_cmp_gt_u32_e64 s[50:51], s34, v107
	v_add_u32_e32 v107, 32, v138
	v_cmp_gt_u32_e64 s[56:57], s34, v107
	v_add_u32_e32 v107, 19, v138
	v_cmp_gt_u32_e64 s[58:59], s34, v107
	v_add_u32_e32 v107, 18, v138
	v_cmp_gt_u32_e64 s[60:61], s34, v107
	v_add_u32_e32 v107, 17, v138
	v_cmp_gt_u32_e64 s[62:63], s34, v107
	v_add_u32_e32 v107, 16, v138
	v_cmp_gt_u32_e64 s[64:65], s34, v107
	v_add_u32_e32 v107, 3, v138
	v_mov_b32_e32 v110, s35
	v_cmp_gt_u32_e64 s[66:67], s34, v107
	v_add_u32_e32 v107, 2, v138
	v_cndmask_b32_e64 v77, v77, v235, s[60:61]
	v_cndmask_b32_e64 v84, v84, v110, s[66:67]
	v_cmp_lt_u32_e64 s[66:67], s38, v107
	v_add_u32_e32 v107, 1, v138
	v_cndmask_b32_e64 v78, v78, v235, s[62:63]
	v_cndmask_b32_e64 v85, v235, v85, s[66:67]
	v_cmp_lt_u32_e64 s[66:67], s38, v107
	v_add_u32_e32 v107, 0x43, v138
	v_cndmask_b32_e64 v79, v79, v235, s[64:65]
	v_cndmask_b32_e64 v86, v235, v86, s[66:67]
	v_cmp_lt_u32_e64 s[66:67], s38, v138
	v_cndmask_b32_e64 v57, v57, v235, s[60:61]
	v_cndmask_b32_e64 v58, v58, v235, s[62:63]
	v_cndmask_b32_e64 v87, v235, v87, s[66:67]
	v_cmp_gt_u32_e64 s[66:67], s34, v107
	v_add_u32_e32 v107, 0x42, v138
	v_readlane_b32 s60, v254, 61
	v_cndmask_b32_e64 v64, v64, v110, s[66:67]
	v_cmp_lt_u32_e64 s[66:67], s38, v107
	v_add_u32_e32 v107, 0x41, v138
	v_cndmask_b32_e64 v59, v59, v235, s[64:65]
	v_cndmask_b32_e64 v65, v235, v65, s[66:67]
	v_cmp_lt_u32_e64 s[66:67], s38, v107
	v_add_u32_e32 v107, 64, v138
	v_readlane_b32 s64, v255, 1
	v_cndmask_b32_e64 v66, v235, v66, s[66:67]
	v_cmp_lt_u32_e64 s[66:67], s38, v107
	v_cndmask_b32_e32 v80, v80, v110, vcc
	v_cndmask_b32_e64 v81, v81, v235, s[0:1]
	v_cndmask_b32_e64 v82, v82, v235, s[42:43]
	v_cndmask_b32_e64 v83, v83, v235, s[44:45]
	v_cndmask_b32_e64 v72, v72, v110, s[46:47]
	v_cndmask_b32_e64 v73, v73, v235, s[48:49]
	v_cndmask_b32_e64 v74, v74, v235, s[50:51]
	v_cndmask_b32_e64 v75, v75, v235, s[56:57]
	v_cndmask_b32_e64 v76, v76, v110, s[58:59]
	v_cndmask_b32_e64 v67, v235, v67, s[66:67]
	v_cndmask_b32_e32 v68, v68, v110, vcc
	v_cndmask_b32_e64 v69, v69, v235, s[0:1]
	v_cndmask_b32_e64 v70, v70, v235, s[42:43]
	v_cndmask_b32_e64 v71, v71, v235, s[44:45]
	v_cndmask_b32_e64 v60, v60, v110, s[46:47]
	v_cndmask_b32_e64 v61, v61, v235, s[48:49]
	v_cndmask_b32_e64 v62, v62, v235, s[50:51]
	v_cndmask_b32_e64 v63, v63, v235, s[56:57]
	v_cndmask_b32_e64 v56, v56, v110, s[58:59]
	v_readlane_b32 s61, v254, 62
	v_readlane_b32 s62, v254, 63
	v_readlane_b32 s63, v255, 0
	v_readlane_b32 s65, v255, 2

.LBB0_382:
	v_mov_b32_e32 v32, v221
	s_movk_i32 s0, 0x800
	s_barrier
	s_nop 0
	v_readfirstlane_b32 s16, v32
	v_cmp_gt_i32_e32 vcc, s0, v32
	v_lshlrev_b32_e32 v33, 3, v32
	s_barrier
	s_and_saveexec_b64 s[0:1], vcc
	v_readlane_b32 s4, v253, 63
	v_readlane_b32 s5, v254, 0
	s_movk_i32 s6, 0x110
	s_movk_i32 s17, 0x5ff
	s_cbranch_execz .LBB0_385
	v_ashrrev_i32_e32 v6, 4, v32
	v_lshlrev_b32_e32 v3, 4, v32
	v_lshlrev_b32_e32 v2, 7, v6
	v_and_b32_e32 v208, 0xf0, v3
	v_ashrrev_i32_e32 v3, 31, v2
	v_lshl_add_u64 v[2:3], v[2:3], 1, s[4:5]
	v_lshl_add_u64 v[20:21], v[2:3], 0, v[208:209]
	s_mov_b32 s10, 0x2000
	s_mov_b32 s11, 0
	v_lshl_add_u64 v[22:23], v[20:21], 0, s[10:11]
	v_lshl_add_u64 v[24:25], v[22:23], 0, s[10:11]
	v_lshl_add_u64 v[26:27], v[24:25], 0, s[10:11]
	global_load_dwordx4 v[2:5], v[20:21], off
	global_load_dwordx4 v[8:11], v[22:23], off
	global_load_dwordx4 v[12:15], v[24:25], off
	global_load_dwordx4 v[16:19], v[26:27], off
	v_mul_lo_u32 v6, v6, s6
	v_add3_u32 v6, 0, v6, v208
	s_waitcnt vmcnt(3)
	ds_write_b128 v6, v[2:5]
	s_waitcnt vmcnt(2)
	ds_write_b128 v6, v[8:11] offset:8704
	s_waitcnt vmcnt(1)
	ds_write_b128 v6, v[12:15] offset:17408
	s_waitcnt vmcnt(0)
	ds_write_b128 v6, v[16:19] offset:26112
	s_nop 0
